# NSA selected-tile loop hand-scheduled: next-tile K-frag prefetch, tile mask folded into MFMA C-init bias, pk_add row sums, setprio on MFMA bursts (also DSA loop)
# speedup vs baseline: 1.1752x; 1.0178x over previous
.LBB0_866:
	v_readlane_b32 s2, v248, 12
	s_lshl_b32 s43, s2, 21
	v_readlane_b32 s2, v248, 6
	v_readlane_b32 s3, v248, 7
	s_lshl_b64 s[40:41], s[2:3], 19
	v_readlane_b32 s2, v248, 25
	v_readlane_b32 s3, v248, 26
	s_or_b32 s42, s43, 0x1800000
	s_lshl_b64 s[38:39], s[2:3], 19
	v_mov_b32_e32 v53, 0
	v_readlane_b32 s2, v248, 14
	s_cmpk_lt_u32 s2, 0xfc
	v_lshl_add_u64 v[156:157], v[136:137], 0, s[38:39]
	v_mov_b32_e32 v52, 0
	s_waitcnt vmcnt(8)
	v_mov_b32_e32 v31, 0
	v_mov_b32_e32 v30, v53
	v_mov_b32_e32 v29, v53
	v_mov_b32_e32 v28, v53
	v_mov_b32_e32 v19, 0
	v_mov_b32_e32 v18, v53
	v_mov_b32_e32 v17, v53
	v_mov_b32_e32 v16, v53
	v_mov_b32_e32 v43, 0
	v_mov_b32_e32 v42, v53
	v_mov_b32_e32 v41, v53
	v_mov_b32_e32 v40, v53
	v_mov_b32_e32 v39, 0
	v_mov_b32_e32 v38, v53
	v_mov_b32_e32 v37, v53
	v_mov_b32_e32 v36, v53
	v_mov_b32_e32 v23, 0
	v_mov_b32_e32 v22, v53
	v_mov_b32_e32 v21, v53
	v_mov_b32_e32 v20, v53
	v_mov_b32_e32 v27, 0
	v_mov_b32_e32 v26, v53
	v_mov_b32_e32 v25, v53
	v_mov_b32_e32 v24, v53
	v_mov_b32_e32 v47, 0
	v_mov_b32_e32 v46, v53
	v_mov_b32_e32 v45, v53
	v_mov_b32_e32 v44, v53
	v_mov_b32_e32 v35, 0
	v_mov_b32_e32 v34, v53
	v_mov_b32_e32 v33, v53
	v_mov_b32_e32 v32, v53
	s_cbranch_scc0 .LBB0_870
	v_readlane_b32 s48, v250, 24
	v_readlane_b32 s49, v250, 25
	v_readlane_b32 s52, v250, 28
	v_readlane_b32 s53, v250, 29
	s_mov_b64 s[48:49], s[52:53]
	s_add_u32 s2, s48, s42
	s_addc_u32 s3, s49, 0
	s_add_u32 s2, s2, s40
	s_addc_u32 s3, s3, s41
	v_lshl_add_u64 v[16:17], s[2:3], 0, v[84:85]
	v_lshl_add_u64 v[158:159], v[16:17], 0, v[116:117]
	s_movk_i32 s3, 0x1000
	v_readlane_b32 s50, v250, 26
	v_add_co_u32_e32 v24, vcc, s3, v158
	global_load_dwordx4 v[16:19], v[158:159], off
	global_load_dwordx4 v[20:23], v[156:157], off
	v_addc_co_u32_e32 v25, vcc, 0, v159, vcc
	s_mov_b32 s50, 0x40000
	v_add_co_u32_e32 v28, vcc, s50, v156
	global_load_dwordx4 v[24:27], v[24:25], off
	s_nop 0
	v_addc_co_u32_e32 v29, vcc, 0, v157, vcc
	global_load_dwordx4 v[28:31], v[28:29], off
	s_cmp_eq_u32 s47, 0
	s_cselect_b32 s2, 0, 64
	s_lshl_b32 s44, s2, 1
	v_mov_b32_e32 v32, 0
	v_readlane_b32 s48, v250, 40
	s_lshr_b32 s46, s48, 1
	v_mov_b32_e32 v33, v32
	v_mov_b32_e32 v34, v32
	v_mov_b32_e32 v35, v32
	v_mov_b32_e32 v44, v32
	v_mov_b32_e32 v45, v32
	v_mov_b32_e32 v46, v32
	v_mov_b32_e32 v47, v32
	v_mov_b32_e32 v36, v32
	v_mov_b32_e32 v37, v32
	v_mov_b32_e32 v38, v32
	v_mov_b32_e32 v39, v32
	v_mov_b32_e32 v40, v32
	v_mov_b32_e32 v41, v32
	v_mov_b32_e32 v42, v32
	v_mov_b32_e32 v43, v32
	v_mov_b32_e32 v160, v32
	v_mov_b32_e32 v161, v32
	v_readlane_b32 s51, v250, 27
	v_readlane_b32 s54, v250, 30
	v_readlane_b32 s55, v250, 31
	v_readlane_b32 s56, v250, 32
	v_readlane_b32 s57, v250, 33
	v_readlane_b32 s58, v250, 34
	v_readlane_b32 s59, v250, 35
	v_readlane_b32 s60, v250, 36
	v_readlane_b32 s61, v250, 37
	v_readlane_b32 s62, v250, 38
	v_readlane_b32 s63, v250, 39
	v_readlane_b32 s49, v250, 41
	s_waitcnt vmcnt(3)
	ds_write_b128 v127, v[16:19]
	s_waitcnt vmcnt(2)
	ds_write_b128 v127, v[20:23] offset:18432
	s_waitcnt vmcnt(1)
	ds_write_b128 v127, v[24:27] offset:4608
	s_waitcnt vmcnt(0)
	ds_write_b128 v127, v[28:31] offset:23040
	v_lshl_add_u64 v[16:17], v[156:157], 0, s[44:45]
	s_lshl_b32 s44, s2, 7
	v_lshl_add_u64 v[18:19], v[158:159], 0, s[44:45]
	global_load_dwordx4 v[52:55], v[18:19], off
	global_load_dwordx4 v[48:51], v[16:17], off
	v_add_co_u32_e32 v18, vcc, s3, v18
	s_mov_b64 s[2:3], 0
	s_nop 0
	v_addc_co_u32_e32 v19, vcc, 0, v19, vcc
	v_add_co_u32_e32 v16, vcc, 0x40000, v16
	global_load_dwordx4 v[56:59], v[18:19], off
	s_nop 0
	v_addc_co_u32_e32 v17, vcc, 0, v17, vcc
	global_load_dwordx4 v[60:63], v[16:17], off
	v_mov_b32_e32 v24, v32
	v_mov_b32_e32 v25, v32
	v_mov_b32_e32 v26, v32
	v_mov_b32_e32 v27, v32
	v_mov_b32_e32 v20, v32
	v_mov_b32_e32 v21, v32
	v_mov_b32_e32 v22, v32
	v_mov_b32_e32 v23, v32
	v_mov_b32_e32 v16, v32
	v_mov_b32_e32 v17, v32
	v_mov_b32_e32 v18, v32
	v_mov_b32_e32 v19, v32
	v_mov_b32_e32 v28, v32
	v_mov_b32_e32 v29, v32
	v_mov_b32_e32 v30, v32
	v_mov_b32_e32 v31, v32
	s_waitcnt lgkmcnt(0)
	s_barrier
	ds_read_b128 v[186:189], v129 offset:0
	ds_read_b128 v[190:193], v129 offset:64
	ds_read_b128 v[194:197], v129 offset:2304
	ds_read_b128 v[198:201], v129 offset:2368
	v_mov_b32_e32 v162, v161
	v_mov_b32_e32 v163, 0
	v_mov_b32_e32 v161, 0
.LBB0_868:
	s_and_b32 s44, s2, 1
	s_xor_b32 s49, s44, 1
	s_mulk_i32 s49, 0x2400
	s_mulk_i32 s44, 0x2400
	v_add_u32_e32 v80, s44, v129
	v_add_u32_e32 v113, s49, v127
	v_add_u32_e32 v76, s44, v167
	ds_read_b128 v[202:205], v80 offset:4608
	ds_read_b128 v[206:209], v80 offset:4672
	ds_read_b128 v[210:213], v80 offset:6912
	ds_read_b128 v[218:221], v80 offset:6976
	v_lshrrev_b64 v[246:247], s2, v[72:73]
	v_lshrrev_b64 v[244:245], s2, v[74:75]
	v_add_u32_e32 v80, s49, v129
	v_not_b32_e32 v246, v246
	v_not_b32_e32 v247, v244
	v_bfe_i32 v246, v246, 0, 1
	v_bfe_i32 v247, v247, 0, 1
	v_and_b32_e32 v238, 0xf149f2ca, v246
	v_and_b32_e32 v242, 0xf149f2ca, v247
	v_and_b32_e32 v239, 0xf149f2ca, v246
	v_and_b32_e32 v243, 0xf149f2ca, v247
	v_and_b32_e32 v240, 0xf149f2ca, v246
	v_and_b32_e32 v244, 0xf149f2ca, v247
	v_and_b32_e32 v241, 0xf149f2ca, v246
	v_and_b32_e32 v245, 0xf149f2ca, v247
	s_setprio 2
	s_waitcnt lgkmcnt(5)
	v_mfma_f32_16x16x32_bf16 v[64:67], v[186:189], v[0:3], v[238:241]
	v_mfma_f32_16x16x32_bf16 v[68:71], v[186:189], v[8:11], v[242:245]
	v_mfma_f32_16x16x32_bf16 v[222:225], v[194:197], v[0:3], v[238:241]
	v_mfma_f32_16x16x32_bf16 v[226:229], v[194:197], v[8:11], v[242:245]
	s_waitcnt vmcnt(2)
	ds_write_b128 v113, v[52:55]
	ds_write_b128 v113, v[48:51] offset:18432
	s_waitcnt lgkmcnt(6)
	v_mfma_f32_16x16x32_bf16 v[64:67], v[190:193], v[4:7], v[64:67]
	v_mfma_f32_16x16x32_bf16 v[68:71], v[190:193], v[12:15], v[68:71]
	v_mfma_f32_16x16x32_bf16 v[222:225], v[198:201], v[4:7], v[222:225]
	v_mfma_f32_16x16x32_bf16 v[226:229], v[198:201], v[12:15], v[226:229]
	s_waitcnt vmcnt(0)
	ds_write_b128 v113, v[56:59] offset:4608
	ds_write_b128 v113, v[60:63] offset:23040
	s_add_i32 s48, s2, 2
	s_min_i32 s48, s48, s47
	s_lshl_b32 s44, s48, 6
	s_lshl_b64 s[48:49], s[44:45], 7
	v_lshl_add_u64 v[52:53], v[158:159], 0, s[48:49]
	v_lshl_add_u64 v[48:49], s[44:45], 1, v[156:157]
	s_or_b32 s44, s44, 32
	s_lshl_b64 s[48:49], s[44:45], 7
	global_load_dwordx4 v[52:55], v[52:53], off
	v_lshl_add_u64 v[56:57], v[158:159], 0, s[48:49]
	v_add_co_u32_e32 v60, vcc, s50, v48
	s_nop 0
	v_addc_co_u32_e32 v61, vcc, 0, v49, vcc
	global_load_dwordx4 v[48:51], v[48:49], off
	global_load_dwordx4 v[56:59], v[56:57], off
	global_load_dwordx4 v[60:63], v[60:61], off
	ds_read_b64 v[186:187], v76 offset:18432
	ds_read_b64 v[188:189], v76 offset:18464
	ds_read_b64 v[190:191], v76 offset:20736
	ds_read_b64 v[192:193], v76 offset:20768
	ds_read_b64 v[194:195], v76 offset:23040
	ds_read_b64 v[196:197], v76 offset:23072
	ds_read_b64 v[198:199], v76 offset:25344
	s_waitcnt lgkmcnt(13)
	ds_read_b64 v[200:201], v76 offset:25376
	s_waitcnt lgkmcnt(13)
	v_mfma_f32_16x16x32_bf16 v[230:233], v[202:205], v[0:3], v[238:241]
	v_mfma_f32_16x16x32_bf16 v[234:237], v[202:205], v[8:11], v[242:245]
	v_mfma_f32_16x16x32_bf16 v[238:241], v[210:213], v[0:3], v[238:241]
	v_mfma_f32_16x16x32_bf16 v[242:245], v[210:213], v[8:11], v[242:245]
	s_waitcnt lgkmcnt(12)
	v_mfma_f32_16x16x32_bf16 v[230:233], v[206:209], v[4:7], v[230:233]
	v_mfma_f32_16x16x32_bf16 v[234:237], v[206:209], v[12:15], v[234:237]
	v_mfma_f32_16x16x32_bf16 v[238:241], v[218:221], v[4:7], v[238:241]
	v_mfma_f32_16x16x32_bf16 v[242:245], v[218:221], v[12:15], v[242:245]
	ds_read_b64 v[202:203], v76 offset:18496
	ds_read_b64 v[204:205], v76 offset:18528
	ds_read_b64 v[206:207], v76 offset:20800
	s_waitcnt lgkmcnt(13)
	ds_read_b64 v[208:209], v76 offset:20832
	ds_read_b64 v[210:211], v76 offset:23104
	s_waitcnt lgkmcnt(13)
	ds_read_b64 v[212:213], v76 offset:23136
	ds_read_b64 v[218:219], v76 offset:25408
	s_waitcnt lgkmcnt(13)
	ds_read_b64 v[220:221], v76 offset:25440
	s_setprio 0
	s_add_u32 s2, s2, 1
	s_addc_u32 s3, s3, 0
	v_exp_f32_e32 v64, v64
	v_exp_f32_e32 v68, v68
	v_exp_f32_e32 v65, v65
	v_exp_f32_e32 v69, v69
	v_exp_f32_e32 v66, v66
	v_exp_f32_e32 v70, v70
	v_exp_f32_e32 v67, v67
	v_exp_f32_e32 v71, v71
	v_pk_add_f32 v[160:161], v[160:161], v[64:65]
	v_pk_add_f32 v[162:163], v[162:163], v[68:69]
	v_pk_add_f32 v[160:161], v[160:161], v[66:67]
	v_pk_add_f32 v[162:163], v[162:163], v[70:71]
	v_exp_f32_e32 v222, v222
	v_exp_f32_e32 v226, v226
	v_exp_f32_e32 v223, v223
	v_exp_f32_e32 v227, v227
	v_exp_f32_e32 v224, v224
	v_exp_f32_e32 v228, v228
	v_exp_f32_e32 v225, v225
	v_exp_f32_e32 v229, v229
	v_pk_add_f32 v[160:161], v[160:161], v[222:223]
	v_pk_add_f32 v[162:163], v[162:163], v[226:227]
	v_pk_add_f32 v[160:161], v[160:161], v[224:225]
	v_pk_add_f32 v[162:163], v[162:163], v[228:229]
	s_waitcnt lgkmcnt(0)
	s_barrier
	v_cvt_pk_bf16_f32 v64, v64, v65
	v_cvt_pk_bf16_f32 v68, v68, v69
	v_cvt_pk_bf16_f32 v65, v66, v67
	v_cvt_pk_bf16_f32 v69, v70, v71
	v_cvt_pk_bf16_f32 v66, v222, v223
	v_cvt_pk_bf16_f32 v70, v226, v227
	v_cvt_pk_bf16_f32 v67, v224, v225
	v_cvt_pk_bf16_f32 v71, v228, v229
	v_exp_f32_e32 v230, v230
	v_exp_f32_e32 v234, v234
	v_mfma_f32_16x16x32_bf16 v[28:31], v[186:189], v[64:67], v[28:31]
	v_exp_f32_e32 v231, v231
	v_exp_f32_e32 v235, v235
	v_exp_f32_e32 v232, v232
	v_exp_f32_e32 v236, v236
	v_mfma_f32_16x16x32_bf16 v[20:23], v[186:189], v[68:71], v[20:23]
	v_exp_f32_e32 v233, v233
	v_exp_f32_e32 v237, v237
	v_pk_add_f32 v[160:161], v[160:161], v[230:231]
	v_pk_add_f32 v[162:163], v[162:163], v[234:235]
	v_mfma_f32_16x16x32_bf16 v[16:19], v[190:193], v[64:67], v[16:19]
	v_pk_add_f32 v[160:161], v[160:161], v[232:233]
	v_pk_add_f32 v[162:163], v[162:163], v[236:237]
	v_exp_f32_e32 v238, v238
	v_exp_f32_e32 v242, v242
	v_mfma_f32_16x16x32_bf16 v[24:27], v[190:193], v[68:71], v[24:27]
	v_exp_f32_e32 v239, v239
	v_exp_f32_e32 v243, v243
	v_exp_f32_e32 v240, v240
	v_exp_f32_e32 v244, v244
	v_mfma_f32_16x16x32_bf16 v[40:43], v[194:197], v[64:67], v[40:43]
	v_exp_f32_e32 v241, v241
	v_exp_f32_e32 v245, v245
	v_pk_add_f32 v[160:161], v[160:161], v[238:239]
	v_pk_add_f32 v[162:163], v[162:163], v[242:243]
	v_mfma_f32_16x16x32_bf16 v[44:47], v[194:197], v[68:71], v[44:47]
	v_pk_add_f32 v[160:161], v[160:161], v[240:241]
	v_pk_add_f32 v[162:163], v[162:163], v[244:245]
	v_cvt_pk_bf16_f32 v230, v230, v231
	v_cvt_pk_bf16_f32 v234, v234, v235
	v_mfma_f32_16x16x32_bf16 v[36:39], v[198:201], v[64:67], v[36:39]
	v_cvt_pk_bf16_f32 v231, v232, v233
	v_cvt_pk_bf16_f32 v235, v236, v237
	v_cvt_pk_bf16_f32 v232, v238, v239
	v_cvt_pk_bf16_f32 v236, v242, v243
	v_mfma_f32_16x16x32_bf16 v[32:35], v[198:201], v[68:71], v[32:35]
	v_cvt_pk_bf16_f32 v233, v240, v241
	v_cvt_pk_bf16_f32 v237, v244, v245
	ds_read_b128 v[186:189], v80 offset:0
	ds_read_b128 v[190:193], v80 offset:64
	ds_read_b128 v[194:197], v80 offset:2304
	ds_read_b128 v[198:201], v80 offset:2368
	s_setprio 2
	v_mfma_f32_16x16x32_bf16 v[28:31], v[202:205], v[230:233], v[28:31]
	v_mfma_f32_16x16x32_bf16 v[20:23], v[202:205], v[234:237], v[20:23]
	v_mfma_f32_16x16x32_bf16 v[16:19], v[206:209], v[230:233], v[16:19]
	v_mfma_f32_16x16x32_bf16 v[24:27], v[206:209], v[234:237], v[24:27]
	v_mfma_f32_16x16x32_bf16 v[40:43], v[210:213], v[230:233], v[40:43]
	v_mfma_f32_16x16x32_bf16 v[44:47], v[210:213], v[234:237], v[44:47]
	v_mfma_f32_16x16x32_bf16 v[36:39], v[218:221], v[230:233], v[36:39]
	v_mfma_f32_16x16x32_bf16 v[32:35], v[218:221], v[234:237], v[32:35]
	s_setprio 0
	s_cmp_lg_u32 s46, s2
	s_cbranch_scc1 .LBB0_868
	s_waitcnt lgkmcnt(0)
	v_add_f32_e32 v160, v160, v161
	v_add_f32_e32 v161, v162, v163
	s_waitcnt vmcnt(3)
	v_mov_b32_e32 v53, v160
	v_mov_b32_e32 v52, v161

.LBB0_885:
	s_and_b32 s41, s39, 1
	s_xor_b32 s42, s41, 1
	s_mul_i32 s43, s42, 0x2400
	v_add_u32_e32 v199, s43, v127
	s_waitcnt vmcnt(4)
	ds_write_b128 v199, v[16:19]
	s_waitcnt vmcnt(3)
	ds_write_b128 v199, v[20:23] offset:18432
	s_waitcnt vmcnt(1)
	ds_write_b128 v199, v[24:27] offset:4608
	s_waitcnt vmcnt(0)
	ds_write_b128 v199, v[28:31] offset:23040
	v_lshl_or_b32 v217, s42, 8, v169
	ds_write_b64 v217, v[152:153] offset:53376
	v_lshl_add_u32 v217, s41, 8, v78
	s_mulk_i32 s41, 0x2400
	v_add_u32_e32 v251, s41, v129
	v_add_u32_e32 v199, s41, v131
	ds_read_b64 v[212:213], v217 offset:53376
	ds_read_b64 v[246:247], v217 offset:53408
	ds_read_b128 v[218:221], v251 offset:0
	ds_read_b128 v[222:225], v251 offset:64
	ds_read_b128 v[226:229], v251 offset:2304
	ds_read_b128 v[230:233], v251 offset:2368
	ds_read_b128 v[234:237], v251 offset:4608
	ds_read_b128 v[238:241], v251 offset:4672
	ds_read_b128 v[242:245], v251 offset:6912
	ds_read_b128 v[200:203], v251 offset:6976
	s_add_i32 s42, s39, 2
	s_min_i32 s42, s42, s38
	s_lshl_b32 s44, s42, 13
	s_lshl_b32 s46, s42, 7
	s_mov_b32 s47, s45
	s_mov_b32 s43, s45
	v_lshl_add_u64 v[16:17], v[148:149], 0, s[44:45]
	v_lshl_add_u64 v[28:29], v[150:151], 0, s[46:47]
	v_lshl_add_u64 v[152:153], s[42:43], 3, v[146:147]
	global_load_dwordx4 v[16:19], v[16:17], off
	global_load_dwordx4 v[20:23], v[28:29], off
	global_load_dwordx2 v[152:153], v[152:153], off
	s_addk_i32 s44, 0x1000
	s_add_i32 s46, s46, 0x40000
	v_lshl_add_u64 v[24:25], v[148:149], 0, s[44:45]
	v_lshl_add_u64 v[28:29], v[150:151], 0, s[46:47]
	global_load_dwordx4 v[24:27], v[24:25], off
	global_load_dwordx4 v[28:31], v[28:29], off
	s_waitcnt lgkmcnt(8)
	v_lshrrev_b32_e32 v212, v112, v212
	v_lshrrev_b32_e32 v213, v112, v213
	v_lshrrev_b32_e32 v246, v112, v246
	v_lshrrev_b32_e32 v247, v112, v247
	s_setprio 2
	s_waitcnt lgkmcnt(7)
	v_mfma_f32_16x16x32_bf16 v[64:67], v[218:221], v[0:3], 0
	v_mfma_f32_16x16x32_bf16 v[68:71], v[218:221], v[8:11], 0
	ds_read_b64 v[194:195], v199 offset:18432
	ds_read_b64 v[196:197], v199 offset:18464
	s_waitcnt lgkmcnt(8)
	v_mfma_f32_16x16x32_bf16 v[64:67], v[222:225], v[4:7], v[64:67]
	v_mfma_f32_16x16x32_bf16 v[68:71], v[222:225], v[12:15], v[68:71]
	s_waitcnt lgkmcnt(7)
	v_mfma_f32_16x16x32_bf16 v[72:75], v[226:229], v[0:3], 0
	v_mfma_f32_16x16x32_bf16 v[156:159], v[226:229], v[8:11], 0
	ds_read_b64 v[204:205], v199 offset:20736
	ds_read_b64 v[206:207], v199 offset:20768
	s_waitcnt lgkmcnt(8)
	v_mfma_f32_16x16x32_bf16 v[72:75], v[230:233], v[4:7], v[72:75]
	v_mfma_f32_16x16x32_bf16 v[156:159], v[230:233], v[12:15], v[156:159]
	s_waitcnt lgkmcnt(7)
	v_mfma_f32_16x16x32_bf16 v[160:163], v[234:237], v[0:3], 0
	v_mfma_f32_16x16x32_bf16 v[182:185], v[234:237], v[8:11], 0
	ds_read_b64 v[208:209], v199 offset:23040
	ds_read_b64 v[210:211], v199 offset:23072
	s_waitcnt lgkmcnt(8)
	v_mfma_f32_16x16x32_bf16 v[160:163], v[238:241], v[4:7], v[160:163]
	v_mfma_f32_16x16x32_bf16 v[182:185], v[238:241], v[12:15], v[182:185]
	ds_read_b64 v[218:219], v199 offset:18496
	ds_read_b64 v[220:221], v199 offset:18528
	ds_read_b64 v[222:223], v199 offset:20800
	ds_read_b64 v[224:225], v199 offset:20832
	s_waitcnt lgkmcnt(11)
	v_mfma_f32_16x16x32_bf16 v[186:189], v[242:245], v[0:3], 0
	v_mfma_f32_16x16x32_bf16 v[190:193], v[242:245], v[8:11], 0
	ds_read_b64 v[84:85], v199 offset:25344
	ds_read_b64 v[86:87], v199 offset:25376
	s_waitcnt lgkmcnt(12)
	v_mfma_f32_16x16x32_bf16 v[186:189], v[200:203], v[4:7], v[186:189]
	v_mfma_f32_16x16x32_bf16 v[190:193], v[200:203], v[12:15], v[190:193]
	ds_read_b64 v[226:227], v199 offset:23104
	ds_read_b64 v[228:229], v199 offset:23136
	ds_read_b64 v[230:231], v199 offset:25408
	s_waitcnt lgkmcnt(13)
	ds_read_b64 v[232:233], v199 offset:25440
	s_setprio 0
	s_waitcnt lgkmcnt(0)
	s_barrier
	v_exp_f32_e32 v64, v64
	v_exp_f32_e32 v68, v68
	v_exp_f32_e32 v65, v65
	v_exp_f32_e32 v69, v69
	v_bfe_i32 v82, v212, 0, 1
	v_bfe_i32 v145, v246, 0, 1
	v_exp_f32_e32 v66, v66
	v_exp_f32_e32 v70, v70
	v_and_b32_e32 v64, v82, v64
	v_and_b32_e32 v68, v145, v68
	v_bfe_i32 v113, v212, 1, 1
	v_bfe_i32 v198, v246, 1, 1
	v_exp_f32_e32 v67, v67
	v_exp_f32_e32 v71, v71
	v_and_b32_e32 v65, v113, v65
	v_and_b32_e32 v69, v198, v69
	v_add_f32_e32 v155, v155, v64
	v_add_f32_e32 v154, v154, v68
	v_bfe_i32 v82, v212, 2, 1
	v_bfe_i32 v145, v246, 2, 1
	v_and_b32_e32 v66, v82, v66
	v_and_b32_e32 v70, v145, v70
	v_add_f32_e32 v155, v155, v65
	v_add_f32_e32 v154, v154, v69
	v_bfe_i32 v113, v212, 3, 1
	v_bfe_i32 v198, v246, 3, 1
	v_and_b32_e32 v67, v113, v67
	v_and_b32_e32 v71, v198, v71
	v_add_f32_e32 v155, v155, v66
	v_add_f32_e32 v154, v154, v70
	v_add_f32_e32 v155, v155, v67
	v_add_f32_e32 v154, v154, v71
	v_exp_f32_e32 v72, v72
	v_exp_f32_e32 v156, v156
	v_exp_f32_e32 v73, v73
	v_exp_f32_e32 v157, v157
	v_bfe_i32 v82, v212, 16, 1
	v_bfe_i32 v145, v246, 16, 1
	v_exp_f32_e32 v74, v74
	v_exp_f32_e32 v158, v158
	v_and_b32_e32 v72, v82, v72
	v_and_b32_e32 v156, v145, v156
	v_bfe_i32 v113, v212, 17, 1
	v_bfe_i32 v198, v246, 17, 1
	v_exp_f32_e32 v75, v75
	v_exp_f32_e32 v159, v159
	v_and_b32_e32 v73, v113, v73
	v_and_b32_e32 v157, v198, v157
	v_add_f32_e32 v155, v155, v72
	v_add_f32_e32 v154, v154, v156
	v_bfe_i32 v82, v212, 18, 1
	v_bfe_i32 v145, v246, 18, 1
	v_and_b32_e32 v74, v82, v74
	v_and_b32_e32 v158, v145, v158
	v_add_f32_e32 v155, v155, v73
	v_add_f32_e32 v154, v154, v157
	v_bfe_i32 v113, v212, 19, 1
	v_bfe_i32 v198, v246, 19, 1
	v_and_b32_e32 v75, v113, v75
	v_and_b32_e32 v159, v198, v159
	v_add_f32_e32 v155, v155, v74
	v_add_f32_e32 v154, v154, v158
	v_add_f32_e32 v155, v155, v75
	v_add_f32_e32 v154, v154, v159
	v_cvt_pk_bf16_f32 v64, v64, v65
	v_cvt_pk_bf16_f32 v68, v68, v69
	v_cvt_pk_bf16_f32 v65, v66, v67
	v_cvt_pk_bf16_f32 v69, v70, v71
	v_cvt_pk_bf16_f32 v66, v72, v73
	v_cvt_pk_bf16_f32 v70, v156, v157
	v_cvt_pk_bf16_f32 v67, v74, v75
	v_cvt_pk_bf16_f32 v71, v158, v159
	v_exp_f32_e32 v160, v160
	v_exp_f32_e32 v182, v182
	v_mfma_f32_16x16x32_bf16 v[36:39], v[194:197], v[64:67], v[36:39]
	v_exp_f32_e32 v161, v161
	v_exp_f32_e32 v183, v183
	v_bfe_i32 v82, v213, 0, 1
	v_bfe_i32 v145, v247, 0, 1
	v_exp_f32_e32 v162, v162
	v_exp_f32_e32 v184, v184
	v_and_b32_e32 v160, v82, v160
	v_and_b32_e32 v182, v145, v182
	v_bfe_i32 v113, v213, 1, 1
	v_mfma_f32_16x16x32_bf16 v[32:35], v[194:197], v[68:71], v[32:35]
	v_bfe_i32 v198, v247, 1, 1
	v_exp_f32_e32 v163, v163
	v_exp_f32_e32 v185, v185
	v_and_b32_e32 v161, v113, v161
	v_and_b32_e32 v183, v198, v183
	v_add_f32_e32 v155, v155, v160
	v_add_f32_e32 v154, v154, v182
	v_bfe_i32 v82, v213, 2, 1
	v_bfe_i32 v145, v247, 2, 1
	v_mfma_f32_16x16x32_bf16 v[60:63], v[204:207], v[64:67], v[60:63]
	v_and_b32_e32 v162, v82, v162
	v_and_b32_e32 v184, v145, v184
	v_add_f32_e32 v155, v155, v161
	v_add_f32_e32 v154, v154, v183
	v_bfe_i32 v113, v213, 3, 1
	v_bfe_i32 v198, v247, 3, 1
	v_and_b32_e32 v163, v113, v163
	v_and_b32_e32 v185, v198, v185
	v_add_f32_e32 v155, v155, v162
	v_mfma_f32_16x16x32_bf16 v[52:55], v[204:207], v[68:71], v[52:55]
	v_add_f32_e32 v154, v154, v184
	v_add_f32_e32 v155, v155, v163
	v_add_f32_e32 v154, v154, v185
	v_exp_f32_e32 v186, v186
	v_exp_f32_e32 v190, v190
	v_exp_f32_e32 v187, v187
	v_exp_f32_e32 v191, v191
	v_bfe_i32 v82, v213, 16, 1
	v_bfe_i32 v145, v247, 16, 1
	v_mfma_f32_16x16x32_bf16 v[56:59], v[208:211], v[64:67], v[56:59]
	v_exp_f32_e32 v188, v188
	v_exp_f32_e32 v192, v192
	v_and_b32_e32 v186, v82, v186
	v_and_b32_e32 v190, v145, v190
	v_bfe_i32 v113, v213, 17, 1
	v_bfe_i32 v198, v247, 17, 1
	v_exp_f32_e32 v189, v189
	v_exp_f32_e32 v193, v193
	v_and_b32_e32 v187, v113, v187
	v_mfma_f32_16x16x32_bf16 v[44:47], v[208:211], v[68:71], v[44:47]
	v_and_b32_e32 v191, v198, v191
	v_add_f32_e32 v155, v155, v186
	v_add_f32_e32 v154, v154, v190
	v_bfe_i32 v82, v213, 18, 1
	v_bfe_i32 v145, v247, 18, 1
	v_and_b32_e32 v188, v82, v188
	v_and_b32_e32 v192, v145, v192
	v_add_f32_e32 v155, v155, v187
	v_add_f32_e32 v154, v154, v191
	v_mfma_f32_16x16x32_bf16 v[48:51], v[84:87], v[64:67], v[48:51]
	v_bfe_i32 v113, v213, 19, 1
	v_bfe_i32 v198, v247, 19, 1
	v_and_b32_e32 v189, v113, v189
	v_and_b32_e32 v193, v198, v193
	v_add_f32_e32 v155, v155, v188
	v_add_f32_e32 v154, v154, v192
	v_add_f32_e32 v155, v155, v189
	v_add_f32_e32 v154, v154, v193
	v_cvt_pk_bf16_f32 v160, v160, v161
	v_mfma_f32_16x16x32_bf16 v[40:43], v[84:87], v[68:71], v[40:43]
	v_cvt_pk_bf16_f32 v182, v182, v183
	v_cvt_pk_bf16_f32 v161, v162, v163
	v_cvt_pk_bf16_f32 v183, v184, v185
	v_cvt_pk_bf16_f32 v162, v186, v187
	v_cvt_pk_bf16_f32 v184, v190, v191
	v_cvt_pk_bf16_f32 v163, v188, v189
	v_cvt_pk_bf16_f32 v185, v192, v193
	s_add_i32 s39, s39, 1
	s_nop 0
	s_setprio 2
	v_mfma_f32_16x16x32_bf16 v[36:39], v[218:221], v[160:163], v[36:39]
	v_mfma_f32_16x16x32_bf16 v[32:35], v[218:221], v[182:185], v[32:35]
	v_mfma_f32_16x16x32_bf16 v[60:63], v[222:225], v[160:163], v[60:63]
	v_mfma_f32_16x16x32_bf16 v[52:55], v[222:225], v[182:185], v[52:55]
	v_mfma_f32_16x16x32_bf16 v[56:59], v[226:229], v[160:163], v[56:59]
	v_mfma_f32_16x16x32_bf16 v[44:47], v[226:229], v[182:185], v[44:47]
	v_mfma_f32_16x16x32_bf16 v[48:51], v[230:233], v[160:163], v[48:51]
	v_mfma_f32_16x16x32_bf16 v[40:43], v[230:233], v[182:185], v[40:43]
	s_setprio 0
	s_cmp_lg_u32 s40, s39
	s_cbranch_scc1 .LBB0_885
	v_lshlrev_b32_e32 v199, 4, v104
	ds_read_b128 v[84:87], v199 offset:54016
	s_waitcnt lgkmcnt(0)
	v_add_u32_e32 v0, s33, v171
	v_or_b32_e32 v0, s2, v0
	v_mov_b32_e32 v1, s3
	v_lshl_add_u64 v[2:3], v[0:1], 0, v[80:81]
	v_lshlrev_b64 v[2:3], 7, v[2:3]
	v_lshl_add_u64 v[2:3], v[142:143], 0, v[2:3]
	global_load_dwordx2 v[4:5], v[2:3], off
	global_load_dwordx2 v[6:7], v[2:3], off offset:32
	global_load_dwordx2 v[8:9], v[2:3], off offset:64
	v_and_b32_e32 v15, 64, v121
	global_load_dwordx2 v[2:3], v[2:3], off offset:96
	v_xor_b32_e32 v14, 16, v121
	v_add_u32_e32 v15, 64, v15
	v_cmp_lt_i32_e32 vcc, v14, v15
	s_waitcnt vmcnt(8)
	v_xor_b32_e32 v16, 32, v121
	v_lshl_add_u64 v[0:1], v[0:1], 0, v[76:77]
	v_cndmask_b32_e32 v14, v121, v14, vcc
	s_waitcnt vmcnt(7)
	v_lshlrev_b32_e32 v20, 2, v14
	ds_bpermute_b32 v14, v20, v155
	v_cmp_lt_i32_e32 vcc, v16, v15
	v_lshlrev_b64 v[0:1], 7, v[0:1]
	v_lshl_add_u64 v[0:1], v[142:143], 0, v[0:1]
	v_cndmask_b32_e32 v15, v121, v16, vcc
	v_lshlrev_b32_e32 v21, 2, v15
	s_waitcnt lgkmcnt(0)
	v_add_f32_e32 v14, v155, v14
	ds_bpermute_b32 v15, v21, v14
	v_readlane_b32 s48, v250, 24
	v_add_u32_e32 v10, s2, v80
	v_mov_b32_e32 v11, v117
	v_readlane_b32 s49, v250, 25
	s_waitcnt lgkmcnt(0)
	v_add_f32_e32 v22, v14, v15
	global_load_dwordx2 v[14:15], v[0:1], off
	global_load_dwordx2 v[16:17], v[0:1], off offset:32
	global_load_dwordx2 v[18:19], v[0:1], off offset:64
	s_nop 0
	global_load_dwordx2 v[0:1], v[0:1], off offset:96
	v_div_scale_f32 v23, s[38:39], v22, v22, 1.0
	s_waitcnt vmcnt(9)
	v_rcp_f32_e32 v24, v23
	v_div_scale_f32 v25, vcc, 1.0, v22, 1.0
	v_readlane_b32 s60, v250, 36
	v_fma_f32 v26, -v23, v24, 1.0
	v_fmac_f32_e32 v24, v26, v24
	v_mul_f32_e32 v26, v25, v24
	v_fma_f32 v27, -v23, v26, v25
	v_fmac_f32_e32 v26, v27, v24
	v_fma_f32 v23, -v23, v26, v25
	v_div_fmas_f32 v23, v23, v24, v26
	v_readlane_b32 s61, v250, 37
	v_div_fixup_f32 v23, v23, v22, 1.0
	v_cmp_lt_f32_e32 vcc, 0, v22
	v_readlane_b32 s3, v248, 12
	v_lshlrev_b64 v[10:11], 11, v[10:11]
	s_mov_b64 s[48:49], s[60:61]
	v_cndmask_b32_e32 v22, 0, v23, vcc
	v_lshl_or_b32 v12, s3, 9, v179
	v_mov_b32_e32 v13, v117
	v_lshl_add_u64 v[10:11], s[48:49], 0, v[10:11]
	v_mul_f32_e32 v23, v36, v22
	v_mul_f32_e32 v24, v37, v22
	v_mul_f32_e32 v26, v39, v22
	v_mov_b32_e32 v145, v117
	v_lshl_add_u64 v[10:11], v[10:11], 0, v[12:13]
	v_mul_f32_e32 v25, v38, v22
	s_waitcnt vmcnt(8)
	v_mul_f32_e32 v28, v61, v22
	v_mul_f32_e32 v30, v63, v22
	v_lshl_add_u64 v[10:11], v[10:11], 0, v[144:145]
	v_mul_f32_e32 v27, v60, v22
	v_mul_f32_e32 v29, v62, v22
	v_mul_f32_e32 v31, v56, v22
	v_readlane_b32 s50, v250, 26
	v_readlane_b32 s51, v250, 27
	v_readlane_b32 s60, v250, 56
	v_readlane_b32 s61, v250, 57
	v_readlane_b32 s50, v248, 20
	v_readlane_b32 s51, v248, 21
	v_readlane_b32 s52, v250, 28
	v_readlane_b32 s53, v250, 29
	v_readlane_b32 s54, v250, 30
	v_readlane_b32 s55, v250, 31
	v_readlane_b32 s56, v250, 32
	v_readlane_b32 s57, v250, 33
	v_readlane_b32 s58, v250, 34
	v_readlane_b32 s59, v250, 35
	v_readlane_b32 s62, v250, 38
	v_readlane_b32 s63, v250, 39
	s_waitcnt vmcnt(7)
	v_lshlrev_b32_e32 v36, 16, v4
	v_and_b32_e32 v4, 0xffff0000, v4
	v_lshlrev_b32_e32 v37, 16, v5
	v_and_b32_e32 v5, 0xffff0000, v5
	s_waitcnt vmcnt(6)
	v_lshlrev_b32_e32 v38, 16, v6
	v_and_b32_e32 v6, 0xffff0000, v6
	v_lshlrev_b32_e32 v39, 16, v7
	v_and_b32_e32 v7, 0xffff0000, v7
	v_mul_f32_e32 v4, v24, v4
	v_mul_f32_e32 v5, v26, v5
	v_mul_f32_e32 v23, v23, v36
	v_mul_f32_e32 v24, v25, v37
	v_mul_f32_e32 v6, v28, v6
	v_mul_f32_e32 v7, v30, v7
	v_cvt_pk_bf16_f32 v4, v23, v4
	v_cvt_pk_bf16_f32 v5, v24, v5
	v_mul_f32_e32 v25, v27, v38
	v_mul_f32_e32 v26, v29, v39
	v_cvt_pk_bf16_f32 v6, v25, v6
	v_cvt_pk_bf16_f32 v7, v26, v7
	global_store_dwordx2 v[10:11], v[4:5], off offset:1024 sc1
	global_store_dwordx2 v[10:11], v[6:7], off offset:1056 sc1
	v_mul_f32_e32 v4, v57, v22
	s_waitcnt vmcnt(7)
	v_and_b32_e32 v5, 0xffff0000, v8
	v_mul_f32_e32 v4, v4, v5
	v_mul_f32_e32 v5, v58, v22
	v_lshlrev_b32_e32 v6, 16, v9
	v_mul_f32_e32 v5, v5, v6
	v_mul_f32_e32 v6, v59, v22
	v_and_b32_e32 v7, 0xffff0000, v9
	v_mul_f32_e32 v6, v6, v7
	v_cvt_pk_bf16_f32 v5, v5, v6
	ds_bpermute_b32 v6, v20, v154
	v_lshlrev_b32_e32 v56, 16, v8
	v_mul_f32_e32 v27, v31, v56
	v_cvt_pk_bf16_f32 v4, v27, v4
	global_store_dwordx2 v[10:11], v[4:5], off offset:1088 sc1
	v_mul_f32_e32 v4, v48, v22
	s_waitcnt vmcnt(7)
	v_lshlrev_b32_e32 v5, 16, v2
	v_mul_f32_e32 v4, v4, v5
	v_mul_f32_e32 v5, v49, v22
	v_and_b32_e32 v2, 0xffff0000, v2
	v_mul_f32_e32 v2, v5, v2
	s_waitcnt lgkmcnt(0)
	v_add_f32_e32 v5, v154, v6
	ds_bpermute_b32 v6, v21, v5
	v_cvt_pk_bf16_f32 v2, v4, v2
	v_mul_f32_e32 v4, v50, v22
	v_lshlrev_b32_e32 v7, 16, v3
	v_mul_f32_e32 v4, v4, v7
	s_waitcnt lgkmcnt(0)
	v_add_f32_e32 v5, v5, v6
	v_div_scale_f32 v6, s[38:39], v5, v5, 1.0
	v_rcp_f32_e32 v8, v6
	v_mul_f32_e32 v7, v51, v22
	v_and_b32_e32 v3, 0xffff0000, v3
	v_mul_f32_e32 v3, v7, v3
	v_cvt_pk_bf16_f32 v3, v4, v3
	global_store_dwordx2 v[10:11], v[2:3], off offset:1120 sc1
	v_fma_f32 v2, -v6, v8, 1.0
	v_fmac_f32_e32 v8, v2, v8
	v_div_scale_f32 v2, vcc, 1.0, v5, 1.0
	v_mul_f32_e32 v3, v2, v8
	v_fma_f32 v4, -v6, v3, v2
	v_fmac_f32_e32 v3, v4, v8
	v_fma_f32 v2, -v6, v3, v2
	v_div_fmas_f32 v2, v2, v8, v3
	v_div_fixup_f32 v2, v2, v5, 1.0
	v_cmp_lt_f32_e32 vcc, 0, v5
	s_waitcnt vmcnt(7)
	v_lshlrev_b32_e32 v5, 16, v14
	v_mov_b32_e32 v3, v117
	v_cndmask_b32_e32 v6, 0, v2, vcc
	v_mul_f32_e32 v4, v32, v6
	v_add_u32_e32 v2, s2, v76
	v_mul_f32_e32 v4, v4, v5
	v_mul_f32_e32 v5, v33, v6
	v_and_b32_e32 v7, 0xffff0000, v14
	v_lshlrev_b64 v[2:3], 11, v[2:3]
	v_mul_f32_e32 v5, v5, v7
	v_lshl_add_u64 v[2:3], s[48:49], 0, v[2:3]
	v_cvt_pk_bf16_f32 v4, v4, v5
	v_mul_f32_e32 v5, v34, v6
	v_lshlrev_b32_e32 v7, 16, v15
	v_lshl_add_u64 v[2:3], v[2:3], 0, v[12:13]
	v_mul_f32_e32 v5, v5, v7
	v_mul_f32_e32 v7, v35, v6
	v_and_b32_e32 v8, 0xffff0000, v15
	v_lshl_add_u64 v[2:3], v[2:3], 0, v[144:145]
	v_mul_f32_e32 v7, v7, v8
	v_cvt_pk_bf16_f32 v5, v5, v7
	global_store_dwordx2 v[2:3], v[4:5], off offset:1024 sc1
	v_mul_f32_e32 v4, v52, v6
	s_waitcnt vmcnt(7)
	v_lshlrev_b32_e32 v5, 16, v16
	v_mul_f32_e32 v4, v4, v5
	v_mul_f32_e32 v5, v53, v6
	v_and_b32_e32 v7, 0xffff0000, v16
	v_mul_f32_e32 v5, v5, v7
	v_cvt_pk_bf16_f32 v4, v4, v5
	v_mul_f32_e32 v5, v54, v6
	v_lshlrev_b32_e32 v7, 16, v17
	v_mul_f32_e32 v5, v5, v7
	v_mul_f32_e32 v7, v55, v6
	v_and_b32_e32 v8, 0xffff0000, v17
	v_mul_f32_e32 v7, v7, v8
	v_cvt_pk_bf16_f32 v5, v5, v7
	global_store_dwordx2 v[2:3], v[4:5], off offset:1056 sc1
	v_mul_f32_e32 v4, v44, v6
	s_waitcnt vmcnt(7)
	v_lshlrev_b32_e32 v5, 16, v18
	v_mul_f32_e32 v4, v4, v5
	v_mul_f32_e32 v5, v45, v6
	v_and_b32_e32 v7, 0xffff0000, v18
	v_mul_f32_e32 v5, v5, v7
	v_cvt_pk_bf16_f32 v4, v4, v5
	v_mul_f32_e32 v5, v46, v6
	v_lshlrev_b32_e32 v7, 16, v19
	v_mul_f32_e32 v5, v5, v7
	v_mul_f32_e32 v7, v47, v6
	v_and_b32_e32 v8, 0xffff0000, v19
	v_mul_f32_e32 v7, v7, v8
	v_cvt_pk_bf16_f32 v5, v5, v7
	global_store_dwordx2 v[2:3], v[4:5], off offset:1088 sc1
	v_mul_f32_e32 v4, v40, v6
	s_waitcnt vmcnt(7)
	v_lshlrev_b32_e32 v5, 16, v0
	v_mul_f32_e32 v4, v4, v5
	v_mul_f32_e32 v5, v41, v6
	v_and_b32_e32 v0, 0xffff0000, v0
	v_mul_f32_e32 v0, v5, v0
	v_cvt_pk_bf16_f32 v0, v4, v0
	v_mul_f32_e32 v4, v42, v6
	v_lshlrev_b32_e32 v5, 16, v1
	v_mul_f32_e32 v4, v4, v5
	v_mul_f32_e32 v5, v43, v6
	v_and_b32_e32 v1, 0xffff0000, v1
	v_mul_f32_e32 v1, v5, v1
	v_cvt_pk_bf16_f32 v1, v4, v1
	global_store_dwordx2 v[2:3], v[0:1], off offset:1120 sc1
	s_waitcnt vmcnt(0)
	s_mov_b64 s[2:3], s[60:61]
	s_barrier
